# v58 + SSD conv*sigmoid output multiplies packed (consumers renamed, symbolically verified) + SSDIn first-iteration vmcnt relax past the previous tile's 16 stores (per-wave flag)
# speedup vs baseline: 1.0175x; 1.0041x over previous
; #define LAS __attribute__((address_space(3)))
; #define PG8_WAIT_V(n) asm volatile("s_waitcnt vmcnt(" #n ")" ::: "memory")
; #define PG8_BAR __builtin_amdgcn_s_barrier()
; template <class Epi, bool ALIGN_EPI = PG8_ALIGN, bool SP2 = PG8_SP2>
; __device__ __forceinline__ void gemm_phase(LAS uchar* lds, const Gemm g, const StaticOrder& S, const Epi& E) {
;     ...
;     unsigned voffA[2], voffB[2];
; #pragma unroll
;     for (int i = 0; i < 2; ++i) { int R, C; stage_rc(tid * 16 + i * 8192, R, C); const int Rb = (R & ~31) + perm32(R & 31);
;         voffA[i] = (unsigned)(R * g.lda + C) * 2u; voffB[i] = (unsigned)(Rb * g.ldb + C) * 2u; }
;     const size_t kstep = (size_t)(BK * 2);
;     const size_t hstepB = (size_t)HALF * g.ldb * 2, hstepA = (size_t)HALF * g.lda * 2;
;     const size_t tstepB = 2 * hstepB, tstepA = 2 * hstepA;
;     const unsigned ldsw = (unsigned)wid * 1024u;
;     const int aoff = lds_byte(wr * 64 + fr, fq * 8), boff = lds_byte(wc * 32 + fr, fq * 8);
;     ...
;     Unit cur, nxt; int ui = 0;
;     if constexpr (Epi::GROUPS) {
;         LAS float* rt = (LAS float*)(lds + LDS_RT);
; #pragma unroll 1
;         for (int u = 0; u < 2; ++u) { Unit uu; if (!S.next(u, uu)) break;
;             if (tid < 256) { const float* sp = g.ssq + (size_t)(uu.pm * 256 + tid) * 16; float r[8];
; #pragma unroll
;                 for (int q = 0; q < 8; ++q) r[q] = rsqrtf((sp[2 * q] + sp[2 * q + 1]) * (1.f / 256.f) + EPS);
; #pragma unroll
;                 for (int q = 0; q < 8; ++q) rt[(u * 256 + tid) * 8 + q] = (q < 7) ? r[q] * __builtin_amdgcn_rcpf(r[q + 1]) : r[7]; } }
;         __syncthreads();
;     }
;     if (!S.next(0, cur)) return;
;     f32x4 acc[2][2][4][2];
; #pragma unroll
;     for (int a = 0; a < 2; ++a)
; #pragma unroll
;         for (int b = 0; b < 2; ++b)
; #pragma unroll
;             for (int m = 0; m < 4; ++m)
; #pragma unroll
;                 for (int n = 0; n < 2; ++n) acc[a][b][m][n] = (f32x4){0.f, 0.f, 0.f, 0.f};
;     bf16x8 At[4][2], B0[2][2], B1[2][2];
;     const char* cA = (const char*)g.A + (size_t)cur.pm * tstepA; const char* cB = (const char*)g.Bt + (size_t)cur.pn * tstepB;
;     if constexpr (SP2) {
;         PG8_STAGE(PG8_SB(0, 0), cB, voffB); PG8_STAGE(PG8_SB(0, 1), cB + hstepB, voffB); PG8_STAGE(PG8_SA(0, 0), cA, voffA); PG8_STAGE(PG8_SA(0, 1), cA + hstepA, voffA);
;         if (wr == 1) PG8_BAR;
;         PG8_WAIT_V(2); PG8_BAR;
.LBB0_332:
	s_mov_b32 s97, 0
	s_mov_b32 s22, s68
	s_waitcnt vmcnt(0)
	v_mov_b32_e32 v18, v136
	s_cmpk_gt_i32 s22, 0xc7f
	v_readfirstlane_b32 s0, v18
	s_cbranch_scc1 .LBB0_358
	v_lshlrev_b32_e32 v1, 4, v18
	s_waitcnt vmcnt(12)
	v_add_u32_e32 v2, 0x2000, v1
	v_ashrrev_i32_e32 v3, 31, v2
	v_lshrrev_b32_e32 v3, 22, v3
	v_add_u32_e32 v3, v2, v3
	s_waitcnt vmcnt(4)
	v_ashrrev_i32_e32 v10, 10, v3
	v_mul_i32_i24_e32 v3, 0x400, v10
	v_sub_u32_e32 v2, v2, v3
	v_lshrrev_b32_e32 v3, 4, v2
	v_bitop3_b32 v2, v3, v2, 32 bitop3:0x6c
	v_ashrrev_i32_e32 v3, 31, v2
	v_lshrrev_b32_e32 v3, 26, v3
	v_add_u32_e32 v3, v2, v3
	v_lshlrev_b32_e32 v4, 3, v10
	v_ashrrev_i32_e32 v11, 6, v3
	v_and_b32_e32 v4, -16, v4
	v_add_u32_e32 v4, v11, v4
	v_and_b32_e32 v5, 3, v11
	s_mov_b32 s5, 0x3ffffe0
	v_lshrrev_b32_e32 v6, 2, v4
	v_lshlrev_b32_e32 v7, 1, v4
	v_and_or_b32 v5, v4, s5, v5
	v_and_b32_e32 v6, 4, v6
	v_and_b32_e32 v7, 24, v7
	v_or3_b32 v5, v5, v6, v7
	v_lshlrev_b32_e32 v6, 5, v10
	v_and_b32_e32 v3, 0xc0, v3
	v_and_b32_e32 v12, 32, v6
	v_sub_u32_e32 v2, v2, v3
	v_mov_b32_e32 v6, 1
	v_ashrrev_i16_sdwa v2, v6, sext(v2) dst_sel:DWORD dst_unused:UNUSED_PAD src0_sel:DWORD src1_sel:BYTE_0
	s_movk_i32 s4, 0x440
	v_bfe_i32 v13, v2, 0, 16
	v_mul_lo_u32 v5, v5, s4
	v_add_u32_e32 v2, v12, v13
	v_mul_lo_u32 v3, v4, s4
	v_add_lshl_u32 v130, v5, v2, 1
	v_add_lshl_u32 v132, v2, v3, 1
	v_bfe_i32 v2, v18, 27, 1
	v_lshrrev_b32_e32 v2, 22, v2
	v_add_u32_e32 v2, v1, v2
	v_and_b32_e32 v2, 0xfffffc00, v2
	v_sub_u32_e32 v1, v1, v2
	v_lshrrev_b32_e32 v2, 4, v1
	v_bitop3_b32 v2, v2, v1, 32 bitop3:0x6c
	v_ashrrev_i32_e32 v1, 31, v1
	v_lshrrev_b32_e32 v1, 26, v1
	v_add_u32_e32 v1, v2, v1
	s_waitcnt vmcnt(0)
	v_ashrrev_i32_e32 v14, 6, v1
	v_ashrrev_i32_e32 v1, 31, v18
	v_lshrrev_b32_e32 v1, 26, v1
	v_add_u32_e32 v1, v18, v1
	v_ashrrev_i32_e32 v15, 6, v1
	v_lshlrev_b32_e32 v1, 3, v15
	v_and_b32_e32 v1, -16, v1
	v_add_u32_e32 v1, v14, v1
	v_and_b32_e32 v3, 3, v14
	v_lshrrev_b32_e32 v4, 2, v1
	v_lshlrev_b32_e32 v5, 1, v1
	v_and_or_b32 v3, v1, s5, v3
	v_and_b32_e32 v4, 4, v4
	v_and_b32_e32 v5, 24, v5
	v_or3_b32 v3, v3, v4, v5
	s_ashr_i32 s24, s22, 31
	v_mul_lo_u32 v3, v3, s4
	v_mul_lo_u32 v1, v1, s4
	s_lshr_b32 s4, s24, 29
	s_add_i32 s4, s22, s4
	s_ashr_i32 s6, s0, 6
	s_ashr_i32 s5, s4, 3
	s_and_b32 s4, s4, -8
	s_ashr_i32 s1, s0, 8
	s_lshl_b32 s23, s6, 10
	s_sub_i32 s4, s22, s4
	s_cmp_lt_i32 s4, 0
	s_movk_i32 s7, 0x191
	s_cselect_b32 s7, s7, 0x190
	s_mul_i32 s4, s7, s4
	s_add_i32 s4, s4, s5
	s_mul_hi_i32 s5, s4, 0x51eb851f
	s_lshr_b32 s7, s5, 31
	s_ashr_i32 s5, s5, 6
	s_add_i32 s5, s5, s7
	s_lshl_b32 s8, s5, 3
	s_mulk_i32 s5, 0xc8
	s_sub_i32 s4, s4, s5
	s_bfe_u32 s5, s4, 0x3001c
	s_add_i32 s5, s4, s5
	s_sext_i32_i16 s9, s5
	s_and_b32 s5, s5, 0xfff8
	v_lshlrev_b32_e32 v4, 5, v15
	s_sub_i32 s4, s4, s5
	v_and_b32_e32 v16, 32, v4
	v_mul_i32_i24_e32 v4, 64, v14
	s_sext_i32_i16 s4, s4
	v_sub_u32_e32 v2, v2, v4
	s_add_i32 s37, s8, s4
	s_ashr_i32 s4, s9, 3
	v_ashrrev_i16_sdwa v2, v6, sext(v2) dst_sel:DWORD dst_unused:UNUSED_PAD src0_sel:DWORD src1_sel:BYTE_0
	s_lshr_b32 s7, s9, 3
	s_mul_hi_i32 s5, s4, 0x88000
	s_mul_i32 s4, s4, 0x88000
	v_readlane_b32 s8, v254, 28
	v_bfe_i32 v17, v2, 0, 16
	v_readlane_b32 s9, v254, 29
	s_add_u32 s4, s8, s4
	v_add_u32_e32 v2, v16, v17
	s_addc_u32 s5, s9, s5
	s_add_i32 s25, s23, 0
	v_add_lshl_u32 v134, v3, v2, 1
	s_add_i32 m0, s25, 0x10000
	v_readlane_b32 s12, v254, 0
	global_load_lds_dwordx4 v134, s[4:5]
	s_add_i32 m0, s25, 0x12000
	s_add_u32 s8, s4, 0x44000
	global_load_lds_dwordx4 v130, s[4:5]
	s_addc_u32 s9, s5, 0
	s_add_i32 m0, s25, 0x14000
	s_mul_i32 s11, s37, 0x88000
	global_load_lds_dwordx4 v134, s[8:9]
	s_add_i32 m0, s25, 0x16000
	v_readlane_b32 s16, v254, 4
	s_mul_hi_i32 s10, s37, 0x88000
	v_readlane_b32 s17, v254, 5
	s_add_u32 s16, s16, s11
	s_addc_u32 s17, s17, s10
	s_add_i32 s26, s25, 0x2000
	v_add_lshl_u32 v156, v2, v1, 1
	global_load_lds_dwordx4 v130, s[8:9]
	s_mov_b32 m0, s25
	s_add_u32 s8, s16, 0x44000
	global_load_lds_dwordx4 v156, s[16:17]
	s_mov_b32 m0, s26
	s_addc_u32 s9, s17, 0
	s_add_i32 s27, s25, 0x4000
	global_load_lds_dwordx4 v132, s[16:17]
	s_mov_b32 m0, s27
	s_add_i32 s28, s25, 0x6000
	global_load_lds_dwordx4 v156, s[8:9]
	s_mov_b32 m0, s28
	v_mov_b32_e32 v135, v0
	global_load_lds_dwordx4 v132, s[8:9]
	v_mov_b32_e32 v131, v0
	v_mov_b32_e32 v157, v0
	v_mov_b32_e32 v133, v0
	s_cmp_eq_u32 s1, 1
	v_mov_b32_e32 v146, 1
	v_lshl_add_u64 v[8:9], s[4:5], 0, v[134:135]
	v_lshl_add_u64 v[6:7], s[4:5], 0, v[130:131]
	v_lshl_add_u64 v[2:3], s[16:17], 0, v[156:157]
	s_cselect_b64 s[8:9], -1, 0
	s_cmp_lg_u32 s1, 1
	v_lshl_add_u64 v[4:5], s[16:17], 0, v[132:133]
	v_readlane_b32 s13, v254, 1
	v_readlane_b32 s14, v254, 2
	v_readlane_b32 s15, v254, 3
	v_readlane_b32 s18, v254, 6
	v_readlane_b32 s19, v254, 7
	s_cbranch_scc1 .LBB0_335
	s_barrier

; #define PG8_STAGE(bufoff, gbase, voff) do { _Pragma("unroll") for (int _i = 0; _i < 2; ++_i) \
;         __builtin_amdgcn_global_load_lds((const unsigned*)((const char*)(gbase) + (voff)[_i]), (LAS unsigned*)(lds + (bufoff) + ldsw + _i * 8192), 16, 0, 0); } while (0)
; #define PG8_LDA(dst, b, h) do { _Pragma("unroll") for (int m = 0; m < 4; ++m) _Pragma("unroll") for (int k = 0; k < 2; ++k) dst[m][k] = *(const LAS bf16x8*)(lds + PG8_SA(b, h) + aoff + m * 2048 + k * 1024); } while (0)
; #define PG8_LDB(dst, b, h) do { _Pragma("unroll") for (int n = 0; n < 2; ++n) _Pragma("unroll") for (int k = 0; k < 2; ++k) dst[n][k] = *(const LAS bf16x8*)(lds + PG8_SB(b, h) + boff + n * 2048 + k * 1024); } while (0)
; #define PG8_MMA(ai, bj, At, Bt) do { __builtin_amdgcn_s_setprio(1); _Pragma("unroll") for (int m = 0; m < 4; ++m) _Pragma("unroll") for (int n = 0; n < 2; ++n) _Pragma("unroll") for (int k = 0; k < 2; ++k) \
;         acc[ai][bj][m][n] = __builtin_amdgcn_mfma_f32_16x16x32_bf16(Bt[n][k], At[m][k], acc[ai][bj][m][n], 0, 0, 0); __builtin_amdgcn_s_setprio(0); } while (0)
; #define PG8_WAIT_V(n) asm volatile("s_waitcnt vmcnt(" #n ")" ::: "memory")
; #define PG8_WAIT_L(n) asm volatile("s_waitcnt lgkmcnt(" #n ")" ::: "memory")
; #define PG8_BAR __builtin_amdgcn_s_barrier()
; #define PG8_SCHED __builtin_amdgcn_sched_barrier(0)
; template <class Epi, bool ALIGN_EPI = PG8_ALIGN, bool SP2 = PG8_SP2>
; __device__ __forceinline__ void gemm_phase(LAS uchar* lds, const Gemm g, const StaticOrder& S, const Epi& E) {
;     ...
;             PG8_LDB(B0, 0, 0); PG8_LDB(B1, 0, 1); PG8_SCHED; PG8_LDA(At, 0, 0); PG8_STAGE(PG8_SA(1, 1), a1 + hstepA, voffA);
;             PG8_WAIT_V(8); PG8_WAIT_L(0); PG8_BAR; PG8_MMA(0, 0, At, B0); PG8_MMA(0, 1, At, B1); PG8_BAR; PG8_SCHED;
.LBB0_345:
	s_add_u32 s18, s16, 0x100
	s_addc_u32 s19, s17, 0
	s_add_i32 s41, 0, 0x10000
	s_cmp_eq_u32 s40, 12
	s_cselect_b32 s21, s7, s19
	s_cselect_b32 s20, s6, s18
	v_add_u32_e32 v168, s41, v139
	s_cselect_b32 s5, s15, s39
	s_cselect_b32 s4, s14, s38
	s_add_i32 s42, 0, 0x14000
	ds_read_b128 v[164:167], v168
	ds_read_b128 v[172:175], v168 offset:1024
	ds_read_b128 v[176:179], v168 offset:2048
	ds_read_b128 v[184:187], v168 offset:3072
	v_add_u32_e32 v168, s42, v139
	ds_read_b128 v[188:191], v168
	ds_read_b128 v[192:195], v168 offset:1024
	ds_read_b128 v[196:199], v168 offset:2048
	ds_read_b128 v[200:203], v168 offset:3072
	v_lshl_add_u64 v[168:169], s[16:17], 0, v[160:161]
	s_add_i32 m0, s25, 0xc000
	ds_read_b128 v[204:207], v171
	ds_read_b128 v[208:211], v171 offset:1024
	ds_read_b128 v[212:215], v171 offset:2048
	ds_read_b128 v[216:219], v171 offset:3072
	ds_read_b128 v[220:223], v171 offset:4096
	ds_read_b128 v[224:227], v171 offset:5120
	ds_read_b128 v[228:231], v171 offset:6144
	ds_read_b128 v[232:235], v171 offset:7168
	global_load_lds_dwordx4 v[168:169], off
	v_lshl_add_u64 v[168:169], s[16:17], 0, v[162:163]
	s_add_i32 m0, s25, 0xe000
	s_nop 0
	global_load_lds_dwordx4 v[168:169], off
	s_cmp_lt_i32 s40, 0
	s_cbranch_scc0 .Lrw_std_345_0
	s_cmp_eq_u32 s97, 1
	s_cbranch_scc0 .Lrw_std_345_0
	s_waitcnt vmcnt(24)
	s_branch .Lrw_done_345_0

; #define PG8_STAGE(bufoff, gbase, voff) do { _Pragma("unroll") for (int _i = 0; _i < 2; ++_i) \
;         __builtin_amdgcn_global_load_lds((const unsigned*)((const char*)(gbase) + (voff)[_i]), (LAS unsigned*)(lds + (bufoff) + ldsw + _i * 8192), 16, 0, 0); } while (0)
; #define PG8_LDA(dst, b, h) do { _Pragma("unroll") for (int m = 0; m < 4; ++m) _Pragma("unroll") for (int k = 0; k < 2; ++k) dst[m][k] = *(const LAS bf16x8*)(lds + PG8_SA(b, h) + aoff + m * 2048 + k * 1024); } while (0)
; #define PG8_MMA(ai, bj, At, Bt) do { __builtin_amdgcn_s_setprio(1); _Pragma("unroll") for (int m = 0; m < 4; ++m) _Pragma("unroll") for (int n = 0; n < 2; ++n) _Pragma("unroll") for (int k = 0; k < 2; ++k) \
;         acc[ai][bj][m][n] = __builtin_amdgcn_mfma_f32_16x16x32_bf16(Bt[n][k], At[m][k], acc[ai][bj][m][n], 0, 0, 0); __builtin_amdgcn_s_setprio(0); } while (0)
; #define PG8_WAIT_V(n) asm volatile("s_waitcnt vmcnt(" #n ")" ::: "memory")
; #define PG8_WAIT_L(n) asm volatile("s_waitcnt lgkmcnt(" #n ")" ::: "memory")
; #define PG8_BAR __builtin_amdgcn_s_barrier()
; #define PG8_SCHED __builtin_amdgcn_sched_barrier(0)
; template <class Epi, bool ALIGN_EPI = PG8_ALIGN, bool SP2 = PG8_SP2>
; __device__ __forceinline__ void gemm_phase(LAS uchar* lds, const Gemm g, const StaticOrder& S, const Epi& E) {
;     ...
;             PG8_WAIT_V(8); PG8_WAIT_L(0); PG8_BAR; PG8_MMA(0, 0, At, B0); PG8_MMA(0, 1, At, B1); PG8_BAR; PG8_SCHED;
;             PG8_LDA(At, 0, 1); PG8_STAGE(PG8_SB(0, 0), b2, voffB); PG8_STAGE(PG8_SB(0, 1), b2 + hstepB, voffB); PG8_STAGE(PG8_SA(0, 0), a2, voffA);
;             PG8_WAIT_V(8); PG8_WAIT_L(0); PG8_BAR; PG8_MMA(1, 0, At, B0); PG8_MMA(1, 1, At, B1); PG8_BAR; PG8_SCHED;
.Lrw_done_345_0:
	s_waitcnt lgkmcnt(0)
	s_barrier
	s_setprio 1
	s_waitcnt lgkmcnt(0)
	v_mfma_f32_16x16x32_bf16 v[126:129], v[164:167], v[204:207], v[126:129]
	v_mfma_f32_16x16x32_bf16 v[122:125], v[176:179], v[204:207], v[122:125]
	v_mfma_f32_16x16x32_bf16 v[118:121], v[164:167], v[212:215], v[118:121]
	v_mfma_f32_16x16x32_bf16 v[110:113], v[176:179], v[212:215], v[110:113]
	v_mfma_f32_16x16x32_bf16 v[102:105], v[164:167], v[220:223], v[102:105]
	v_mfma_f32_16x16x32_bf16 v[94:97], v[176:179], v[220:223], v[94:97]
	v_mfma_f32_16x16x32_bf16 v[86:89], v[164:167], v[228:231], v[86:89]
	v_mfma_f32_16x16x32_bf16 v[78:81], v[176:179], v[228:231], v[78:81]
	v_mfma_f32_16x16x32_bf16 v[126:129], v[172:175], v[208:211], v[126:129]
	v_mfma_f32_16x16x32_bf16 v[122:125], v[184:187], v[208:211], v[122:125]
	v_mfma_f32_16x16x32_bf16 v[118:121], v[172:175], v[216:219], v[118:121]
	v_mfma_f32_16x16x32_bf16 v[110:113], v[184:187], v[216:219], v[110:113]
	v_mfma_f32_16x16x32_bf16 v[102:105], v[172:175], v[224:227], v[102:105]
	v_mfma_f32_16x16x32_bf16 v[94:97], v[184:187], v[224:227], v[94:97]
	v_mfma_f32_16x16x32_bf16 v[86:89], v[172:175], v[232:235], v[86:89]
	v_mfma_f32_16x16x32_bf16 v[78:81], v[184:187], v[232:235], v[78:81]
	s_setprio 0
	s_setprio 1
	v_mfma_f32_16x16x32_bf16 v[114:117], v[188:191], v[204:207], v[114:117]
	v_mfma_f32_16x16x32_bf16 v[106:109], v[196:199], v[204:207], v[106:109]
	v_mfma_f32_16x16x32_bf16 v[98:101], v[188:191], v[212:215], v[98:101]
	v_mfma_f32_16x16x32_bf16 v[90:93], v[196:199], v[212:215], v[90:93]
	v_mfma_f32_16x16x32_bf16 v[82:85], v[188:191], v[220:223], v[82:85]
	v_mfma_f32_16x16x32_bf16 v[74:77], v[196:199], v[220:223], v[74:77]
	v_mfma_f32_16x16x32_bf16 v[70:73], v[188:191], v[228:231], v[70:73]
	v_mfma_f32_16x16x32_bf16 v[66:69], v[196:199], v[228:231], v[66:69]
	v_mfma_f32_16x16x32_bf16 v[114:117], v[192:195], v[208:211], v[114:117]
	v_mfma_f32_16x16x32_bf16 v[106:109], v[200:203], v[208:211], v[106:109]
	v_mfma_f32_16x16x32_bf16 v[98:101], v[192:195], v[216:219], v[98:101]
	v_mfma_f32_16x16x32_bf16 v[90:93], v[200:203], v[216:219], v[90:93]
	v_mfma_f32_16x16x32_bf16 v[82:85], v[192:195], v[224:227], v[82:85]
	v_mfma_f32_16x16x32_bf16 v[74:77], v[200:203], v[224:227], v[74:77]
	v_mfma_f32_16x16x32_bf16 v[70:73], v[192:195], v[232:235], v[70:73]
	v_mfma_f32_16x16x32_bf16 v[66:69], v[200:203], v[232:235], v[66:69]
	s_setprio 0
	s_barrier
	s_add_i32 s16, s41, s23
	v_lshl_add_u64 v[168:169], s[4:5], 0, v[134:135]
	s_mov_b32 m0, s16
	ds_read_b128 v[204:207], v171 offset:16384
	ds_read_b128 v[208:211], v171 offset:17408
	ds_read_b128 v[212:215], v171 offset:18432
	ds_read_b128 v[216:219], v171 offset:19456
	ds_read_b128 v[220:223], v171 offset:20480
	ds_read_b128 v[224:227], v171 offset:21504
	ds_read_b128 v[228:231], v171 offset:22528
	ds_read_b128 v[232:235], v171 offset:23552
	global_load_lds_dwordx4 v[168:169], off
	s_add_i32 m0, s16, 0x2000
	s_add_u32 s16, s4, 0x44000
	v_lshl_add_u64 v[180:181], s[4:5], 0, v[130:131]
	s_addc_u32 s17, s5, 0
	s_add_i32 s41, s42, s23
	global_load_lds_dwordx4 v[180:181], off
	v_lshl_add_u64 v[236:237], s[16:17], 0, v[134:135]
	s_mov_b32 m0, s41
	v_lshl_add_u64 v[238:239], s[20:21], 0, v[132:133]
	global_load_lds_dwordx4 v[236:237], off
	v_lshl_add_u64 v[236:237], s[16:17], 0, v[130:131]
	s_add_i32 m0, s41, 0x2000
	s_nop 0
	global_load_lds_dwordx4 v[236:237], off
	v_lshl_add_u64 v[236:237], s[20:21], 0, v[156:157]
	s_mov_b32 m0, s25
	s_nop 0
	global_load_lds_dwordx4 v[236:237], off
	s_mov_b32 m0, s26
	s_nop 0
	global_load_lds_dwordx4 v[238:239], off
	s_cmp_lt_i32 s40, 0
	s_cbranch_scc0 .Lrw_std_345_1
	s_cmp_eq_u32 s97, 1
	s_cbranch_scc0 .Lrw_std_345_1
	s_waitcnt vmcnt(24)
	s_branch .Lrw_done_345_1

; #define PG8_STAGE(bufoff, gbase, voff) do { _Pragma("unroll") for (int _i = 0; _i < 2; ++_i) \
;         __builtin_amdgcn_global_load_lds((const unsigned*)((const char*)(gbase) + (voff)[_i]), (LAS unsigned*)(lds + (bufoff) + ldsw + _i * 8192), 16, 0, 0); } while (0)
; #define PG8_LDA(dst, b, h) do { _Pragma("unroll") for (int m = 0; m < 4; ++m) _Pragma("unroll") for (int k = 0; k < 2; ++k) dst[m][k] = *(const LAS bf16x8*)(lds + PG8_SA(b, h) + aoff + m * 2048 + k * 1024); } while (0)
; #define PG8_LDB(dst, b, h) do { _Pragma("unroll") for (int n = 0; n < 2; ++n) _Pragma("unroll") for (int k = 0; k < 2; ++k) dst[n][k] = *(const LAS bf16x8*)(lds + PG8_SB(b, h) + boff + n * 2048 + k * 1024); } while (0)
; #define PG8_MMA(ai, bj, At, Bt) do { __builtin_amdgcn_s_setprio(1); _Pragma("unroll") for (int m = 0; m < 4; ++m) _Pragma("unroll") for (int n = 0; n < 2; ++n) _Pragma("unroll") for (int k = 0; k < 2; ++k) \
;         acc[ai][bj][m][n] = __builtin_amdgcn_mfma_f32_16x16x32_bf16(Bt[n][k], At[m][k], acc[ai][bj][m][n], 0, 0, 0); __builtin_amdgcn_s_setprio(0); } while (0)
; #define PG8_WAIT_V(n) asm volatile("s_waitcnt vmcnt(" #n ")" ::: "memory")
; #define PG8_WAIT_L(n) asm volatile("s_waitcnt lgkmcnt(" #n ")" ::: "memory")
; #define PG8_BAR __builtin_amdgcn_s_barrier()
; #define PG8_SCHED __builtin_amdgcn_sched_barrier(0)
; template <class Epi, bool ALIGN_EPI = PG8_ALIGN, bool SP2 = PG8_SP2>
; __device__ __forceinline__ void gemm_phase(LAS uchar* lds, const Gemm g, const StaticOrder& S, const Epi& E) {
;     ...
;             PG8_WAIT_V(8); PG8_WAIT_L(0); PG8_BAR; PG8_MMA(1, 0, At, B0); PG8_MMA(1, 1, At, B1); PG8_BAR; PG8_SCHED;
;             PG8_LDB(B0, 1, 0); PG8_LDB(B1, 1, 1); PG8_SCHED; PG8_LDA(At, 1, 0); PG8_STAGE(PG8_SA(0, 1), a2 + hstepA, voffA);
;             PG8_WAIT_V(8); PG8_WAIT_L(0); PG8_BAR; PG8_MMA(0, 0, At, B0); PG8_MMA(0, 1, At, B1); PG8_BAR; PG8_SCHED;
.Lrw_done_345_1:
	s_waitcnt lgkmcnt(0)
	s_barrier
	s_setprio 1
	s_waitcnt lgkmcnt(0)
	v_mfma_f32_16x16x32_bf16 v[62:65], v[164:167], v[204:207], v[62:65]
	v_mfma_f32_16x16x32_bf16 v[58:61], v[176:179], v[204:207], v[58:61]
	v_mfma_f32_16x16x32_bf16 v[54:57], v[164:167], v[212:215], v[54:57]
	v_mfma_f32_16x16x32_bf16 v[46:49], v[176:179], v[212:215], v[46:49]
	v_mfma_f32_16x16x32_bf16 v[38:41], v[164:167], v[220:223], v[38:41]
	v_mfma_f32_16x16x32_bf16 v[30:33], v[176:179], v[220:223], v[30:33]
	v_mfma_f32_16x16x32_bf16 v[22:25], v[164:167], v[228:231], v[22:25]
	v_mfma_f32_16x16x32_bf16 v[14:17], v[176:179], v[228:231], v[14:17]
	v_mfma_f32_16x16x32_bf16 v[62:65], v[172:175], v[208:211], v[62:65]
	v_mfma_f32_16x16x32_bf16 v[58:61], v[184:187], v[208:211], v[58:61]
	v_mfma_f32_16x16x32_bf16 v[54:57], v[172:175], v[216:219], v[54:57]
	v_mfma_f32_16x16x32_bf16 v[46:49], v[184:187], v[216:219], v[46:49]
	v_mfma_f32_16x16x32_bf16 v[38:41], v[172:175], v[224:227], v[38:41]
	v_mfma_f32_16x16x32_bf16 v[30:33], v[184:187], v[224:227], v[30:33]
	v_mfma_f32_16x16x32_bf16 v[22:25], v[172:175], v[232:235], v[22:25]
	v_mfma_f32_16x16x32_bf16 v[14:17], v[184:187], v[232:235], v[14:17]
	s_setprio 0
	s_setprio 1
	v_mfma_f32_16x16x32_bf16 v[50:53], v[188:191], v[204:207], v[50:53]
	v_mfma_f32_16x16x32_bf16 v[42:45], v[196:199], v[204:207], v[42:45]
	v_mfma_f32_16x16x32_bf16 v[34:37], v[188:191], v[212:215], v[34:37]
	v_mfma_f32_16x16x32_bf16 v[26:29], v[196:199], v[212:215], v[26:29]
	v_mfma_f32_16x16x32_bf16 v[18:21], v[188:191], v[220:223], v[18:21]
	v_mfma_f32_16x16x32_bf16 v[10:13], v[196:199], v[220:223], v[10:13]
	v_mfma_f32_16x16x32_bf16 v[6:9], v[188:191], v[228:231], v[6:9]
	v_mfma_f32_16x16x32_bf16 v[2:5], v[196:199], v[228:231], v[2:5]
	v_mfma_f32_16x16x32_bf16 v[50:53], v[192:195], v[208:211], v[50:53]
	v_mfma_f32_16x16x32_bf16 v[42:45], v[200:203], v[208:211], v[42:45]
	v_mfma_f32_16x16x32_bf16 v[34:37], v[192:195], v[216:219], v[34:37]
	v_mfma_f32_16x16x32_bf16 v[26:29], v[200:203], v[216:219], v[26:29]
	v_mfma_f32_16x16x32_bf16 v[18:21], v[192:195], v[224:227], v[18:21]
	v_mfma_f32_16x16x32_bf16 v[10:13], v[200:203], v[224:227], v[10:13]
	v_mfma_f32_16x16x32_bf16 v[6:9], v[192:195], v[232:235], v[6:9]
	v_mfma_f32_16x16x32_bf16 v[2:5], v[200:203], v[232:235], v[2:5]
	s_setprio 0
	s_barrier
	s_add_i32 s41, 0, 0x18000
	s_add_i32 s42, 0, 0x1c000
	v_add_u32_e32 v184, s41, v139
	v_add_u32_e32 v200, s42, v139
	ds_read_b128 v[164:167], v184
	ds_read_b128 v[172:175], v184 offset:1024
	ds_read_b128 v[176:179], v184 offset:2048
	ds_read_b128 v[184:187], v184 offset:3072
	ds_read_b128 v[188:191], v200
	ds_read_b128 v[192:195], v200 offset:1024
	ds_read_b128 v[196:199], v200 offset:2048
	ds_read_b128 v[200:203], v200 offset:3072
	s_add_u32 s16, s20, 0x44000
	s_addc_u32 s17, s21, 0
	s_mov_b32 m0, s27
	v_lshl_add_u64 v[240:241], s[16:17], 0, v[156:157]
	ds_read_b128 v[204:207], v171 offset:32768
	ds_read_b128 v[208:211], v171 offset:33792
	ds_read_b128 v[212:215], v171 offset:34816
	ds_read_b128 v[216:219], v171 offset:35840
	ds_read_b128 v[220:223], v171 offset:36864
	ds_read_b128 v[224:227], v171 offset:37888
	ds_read_b128 v[228:231], v171 offset:38912
	ds_read_b128 v[232:235], v171 offset:39936
	global_load_lds_dwordx4 v[240:241], off
	v_lshl_add_u64 v[240:241], s[16:17], 0, v[132:133]
	s_mov_b32 m0, s28
	s_nop 0
	global_load_lds_dwordx4 v[240:241], off
	s_waitcnt vmcnt(8)
	s_waitcnt lgkmcnt(0)
	s_barrier
	s_setprio 1
	s_waitcnt lgkmcnt(0)
	v_mfma_f32_16x16x32_bf16 v[126:129], v[164:167], v[204:207], v[126:129]
	v_mfma_f32_16x16x32_bf16 v[122:125], v[176:179], v[204:207], v[122:125]
	v_mfma_f32_16x16x32_bf16 v[118:121], v[164:167], v[212:215], v[118:121]
	v_mfma_f32_16x16x32_bf16 v[110:113], v[176:179], v[212:215], v[110:113]
	v_mfma_f32_16x16x32_bf16 v[102:105], v[164:167], v[220:223], v[102:105]
	v_mfma_f32_16x16x32_bf16 v[94:97], v[176:179], v[220:223], v[94:97]
	v_mfma_f32_16x16x32_bf16 v[86:89], v[164:167], v[228:231], v[86:89]
	v_mfma_f32_16x16x32_bf16 v[78:81], v[176:179], v[228:231], v[78:81]
	v_mfma_f32_16x16x32_bf16 v[126:129], v[172:175], v[208:211], v[126:129]
	v_mfma_f32_16x16x32_bf16 v[122:125], v[184:187], v[208:211], v[122:125]
	v_mfma_f32_16x16x32_bf16 v[118:121], v[172:175], v[216:219], v[118:121]
	v_mfma_f32_16x16x32_bf16 v[110:113], v[184:187], v[216:219], v[110:113]
	v_mfma_f32_16x16x32_bf16 v[102:105], v[172:175], v[224:227], v[102:105]
	v_mfma_f32_16x16x32_bf16 v[94:97], v[184:187], v[224:227], v[94:97]
	v_mfma_f32_16x16x32_bf16 v[86:89], v[172:175], v[232:235], v[86:89]
	v_mfma_f32_16x16x32_bf16 v[78:81], v[184:187], v[232:235], v[78:81]
	s_setprio 0
	s_setprio 1
	v_mfma_f32_16x16x32_bf16 v[114:117], v[188:191], v[204:207], v[114:117]
	v_mfma_f32_16x16x32_bf16 v[106:109], v[196:199], v[204:207], v[106:109]
	v_mfma_f32_16x16x32_bf16 v[98:101], v[188:191], v[212:215], v[98:101]
	v_mfma_f32_16x16x32_bf16 v[90:93], v[196:199], v[212:215], v[90:93]
	v_mfma_f32_16x16x32_bf16 v[82:85], v[188:191], v[220:223], v[82:85]
	v_mfma_f32_16x16x32_bf16 v[74:77], v[196:199], v[220:223], v[74:77]
	v_mfma_f32_16x16x32_bf16 v[70:73], v[188:191], v[228:231], v[70:73]
	v_mfma_f32_16x16x32_bf16 v[66:69], v[196:199], v[228:231], v[66:69]
	v_mfma_f32_16x16x32_bf16 v[114:117], v[192:195], v[208:211], v[114:117]
	v_mfma_f32_16x16x32_bf16 v[106:109], v[200:203], v[208:211], v[106:109]
	v_mfma_f32_16x16x32_bf16 v[98:101], v[192:195], v[216:219], v[98:101]
	v_mfma_f32_16x16x32_bf16 v[90:93], v[200:203], v[216:219], v[90:93]
	v_mfma_f32_16x16x32_bf16 v[82:85], v[192:195], v[224:227], v[82:85]
	v_mfma_f32_16x16x32_bf16 v[74:77], v[200:203], v[224:227], v[74:77]
	v_mfma_f32_16x16x32_bf16 v[70:73], v[192:195], v[232:235], v[70:73]
	v_mfma_f32_16x16x32_bf16 v[66:69], v[200:203], v[232:235], v[66:69]
	s_setprio 0
	s_barrier
; __device__ __forceinline__ unsigned pk2(float lo, float hi) { unsigned r; asm("v_cvt_pk_bf16_f32 %0, %1, %2" : "=v"(r) : "v"(lo), "v"(hi)); return r; }
; #define PG8_STAGE(bufoff, gbase, voff) do { _Pragma("unroll") for (int _i = 0; _i < 2; ++_i) \
;         __builtin_amdgcn_global_load_lds((const unsigned*)((const char*)(gbase) + (voff)[_i]), (LAS unsigned*)(lds + (bufoff) + ldsw + _i * 8192), 16, 0, 0); } while (0)
; #define PG8_LDA(dst, b, h) do { _Pragma("unroll") for (int m = 0; m < 4; ++m) _Pragma("unroll") for (int k = 0; k < 2; ++k) dst[m][k] = *(const LAS bf16x8*)(lds + PG8_SA(b, h) + aoff + m * 2048 + k * 1024); } while (0)
; #define PG8_MMA(ai, bj, At, Bt) do { __builtin_amdgcn_s_setprio(1); _Pragma("unroll") for (int m = 0; m < 4; ++m) _Pragma("unroll") for (int n = 0; n < 2; ++n) _Pragma("unroll") for (int k = 0; k < 2; ++k) \
;         acc[ai][bj][m][n] = __builtin_amdgcn_mfma_f32_16x16x32_bf16(Bt[n][k], At[m][k], acc[ai][bj][m][n], 0, 0, 0); __builtin_amdgcn_s_setprio(0); } while (0)
; #define PG8_WAIT_V(n) asm volatile("s_waitcnt vmcnt(" #n ")" ::: "memory")
; template <class Epi, bool ALIGN_EPI = PG8_ALIGN, bool SP2 = PG8_SP2>
; __device__ __forceinline__ void gemm_phase(LAS uchar* lds, const Gemm g, const StaticOrder& S, const Epi& E) {
;     ...
;             PG8_LDA(At, 1, 1); PG8_STAGE(PG8_SB(1, 0), b3, voffB); PG8_STAGE(PG8_SB(1, 1), b3 + hstepB, voffB); PG8_STAGE(PG8_SA(1, 0), a3, voffA);
;             PG8_WAIT_V(8); PG8_WAIT_L(0); PG8_BAR; PG8_MMA(1, 0, At, B0); PG8_MMA(1, 1, At, B1); PG8_BAR; PG8_SCHED;
;     __device__ __forceinline__ void operator()(const f32x4 (&acc)[2][2][4][2], const pg8::Unit& u, int wr, int wc, int fr, int fq, int) const {
;         const int row0 = u.pm * 256 + wr * 64 + fr;
;         if (u.pn < 24) {
;             const int col0 = u.pn * 256 + wc * 32 + 8 * fq;
; #pragma unroll
;             for (int ai = 0; ai < 2; ++ai)
; #pragma unroll
;                 for (int m = 0; m < 4; ++m) { bf16_t* rowp = ZX + (size_t)(row0 + ai * 128 + m * 16) * LDZ + col0;
; #pragma unroll
;                     for (int bj = 0; bj < 2; ++bj) { const f32x4 v0 = acc[ai][bj][m][0], v1 = acc[ai][bj][m][1];
;                         u32x4 o; o.x = pk2(v0[0], v0[1]); o.y = pk2(v0[2], v0[3]); o.z = pk2(v1[0], v1[1]); o.w = pk2(v1[2], v1[3]);
;                         *(u32x4*)(rowp + bj * 128) = o; } }
;         } else if (wc == 0) {
	s_add_i32 s16, s41, s23
	v_lshl_add_u64 v[168:169], v[168:169], 0, s[84:85]
	s_mov_b32 m0, s16
	ds_read_b128 v[204:207], v171 offset:49152
	ds_read_b128 v[208:211], v171 offset:50176
	ds_read_b128 v[212:215], v171 offset:51200
	ds_read_b128 v[216:219], v171 offset:52224
	ds_read_b128 v[220:223], v171 offset:53248
	ds_read_b128 v[224:227], v171 offset:54272
	ds_read_b128 v[228:231], v171 offset:55296
	ds_read_b128 v[232:235], v171 offset:56320
	global_load_lds_dwordx4 v[168:169], off
	s_add_i32 m0, s16, 0x2000
	s_add_u32 s4, s4, 0x44080
	v_lshl_add_u64 v[168:169], v[180:181], 0, s[84:85]
	s_addc_u32 s5, s5, 0
	s_add_i32 s16, s42, s23
	global_load_lds_dwordx4 v[168:169], off
	v_lshl_add_u64 v[168:169], s[4:5], 0, v[134:135]
	s_mov_b32 m0, s16
	s_nop 0
	global_load_lds_dwordx4 v[168:169], off
	v_lshl_add_u64 v[168:169], s[4:5], 0, v[130:131]
	s_add_i32 m0, s16, 0x2000
	s_nop 0
	global_load_lds_dwordx4 v[168:169], off
	v_lshl_add_u64 v[168:169], v[236:237], 0, s[84:85]
	s_mov_b32 m0, s29
	s_nop 0
	global_load_lds_dwordx4 v[168:169], off
	v_lshl_add_u64 v[168:169], v[238:239], 0, s[84:85]
	s_mov_b32 m0, s30
	s_nop 0
	global_load_lds_dwordx4 v[168:169], off
	s_waitcnt vmcnt(8)
	s_waitcnt lgkmcnt(0)
	s_barrier
	s_setprio 1
	s_waitcnt lgkmcnt(0)
	v_mfma_f32_16x16x32_bf16 v[62:65], v[164:167], v[204:207], v[62:65]
	v_mfma_f32_16x16x32_bf16 v[58:61], v[176:179], v[204:207], v[58:61]
	v_mfma_f32_16x16x32_bf16 v[54:57], v[164:167], v[212:215], v[54:57]
	v_mfma_f32_16x16x32_bf16 v[46:49], v[176:179], v[212:215], v[46:49]
	v_mfma_f32_16x16x32_bf16 v[38:41], v[164:167], v[220:223], v[38:41]
	v_mfma_f32_16x16x32_bf16 v[30:33], v[176:179], v[220:223], v[30:33]
	v_mfma_f32_16x16x32_bf16 v[22:25], v[164:167], v[228:231], v[22:25]
	v_mfma_f32_16x16x32_bf16 v[14:17], v[176:179], v[228:231], v[14:17]
	v_mfma_f32_16x16x32_bf16 v[62:65], v[172:175], v[208:211], v[62:65]
	v_mfma_f32_16x16x32_bf16 v[58:61], v[184:187], v[208:211], v[58:61]
	v_mfma_f32_16x16x32_bf16 v[54:57], v[172:175], v[216:219], v[54:57]
	v_mfma_f32_16x16x32_bf16 v[46:49], v[184:187], v[216:219], v[46:49]
	v_mfma_f32_16x16x32_bf16 v[38:41], v[172:175], v[224:227], v[38:41]
	v_mfma_f32_16x16x32_bf16 v[30:33], v[184:187], v[224:227], v[30:33]
	v_mfma_f32_16x16x32_bf16 v[22:25], v[172:175], v[232:235], v[22:25]
	v_mfma_f32_16x16x32_bf16 v[14:17], v[184:187], v[232:235], v[14:17]
	s_setprio 0
	s_setprio 1
	v_mfma_f32_16x16x32_bf16 v[50:53], v[188:191], v[204:207], v[50:53]
	v_mfma_f32_16x16x32_bf16 v[42:45], v[196:199], v[204:207], v[42:45]
	v_mfma_f32_16x16x32_bf16 v[34:37], v[188:191], v[212:215], v[34:37]
	v_mfma_f32_16x16x32_bf16 v[26:29], v[196:199], v[212:215], v[26:29]
	v_mfma_f32_16x16x32_bf16 v[18:21], v[188:191], v[220:223], v[18:21]
	v_mfma_f32_16x16x32_bf16 v[10:13], v[196:199], v[220:223], v[10:13]
	v_mfma_f32_16x16x32_bf16 v[6:9], v[188:191], v[228:231], v[6:9]
	v_mfma_f32_16x16x32_bf16 v[2:5], v[196:199], v[228:231], v[2:5]
	v_mfma_f32_16x16x32_bf16 v[50:53], v[192:195], v[208:211], v[50:53]
	v_mfma_f32_16x16x32_bf16 v[42:45], v[200:203], v[208:211], v[42:45]
	v_mfma_f32_16x16x32_bf16 v[34:37], v[192:195], v[216:219], v[34:37]
	v_mfma_f32_16x16x32_bf16 v[26:29], v[200:203], v[216:219], v[26:29]
	v_mfma_f32_16x16x32_bf16 v[18:21], v[192:195], v[224:227], v[18:21]
	v_mfma_f32_16x16x32_bf16 v[10:13], v[200:203], v[224:227], v[10:13]
	v_mfma_f32_16x16x32_bf16 v[6:9], v[192:195], v[232:235], v[6:9]
	v_mfma_f32_16x16x32_bf16 v[2:5], v[200:203], v[232:235], v[2:5]
	s_setprio 0
	s_barrier
	s_add_i32 s40, s40, 2
	s_add_u32 s38, s38, 0x100
	s_addc_u32 s39, s39, 0
	s_cmp_gt_u32 s40, 13
	s_mov_b64 s[16:17], s[18:19]
	s_cbranch_scc0 .LBB0_345
	s_mov_b32 s97, 0
	s_and_b64 vcc, exec, s[10:11]
	s_cbranch_vccnz .LBB0_350
	v_lshl_add_u32 v164, s37, 8, v1
	s_cmp_gt_i32 s36, 23
	s_mov_b64 s[4:5], -1
	s_cbranch_scc1 .LBB0_351

; __device__ __forceinline__ unsigned pk2(float lo, float hi) { unsigned r; asm("v_cvt_pk_bf16_f32 %0, %1, %2" : "=v"(r) : "v"(lo), "v"(hi)); return r; }
;     __device__ __forceinline__ void operator()(const f32x4 (&acc)[2][2][4][2], const pg8::Unit& u, int wr, int wc, int fr, int fq, int) const {
;         const int row0 = u.pm * 256 + wr * 64 + fr;
;         if (u.pn < 24) {
;             const int col0 = u.pn * 256 + wc * 32 + 8 * fq;
; #pragma unroll
;             for (int ai = 0; ai < 2; ++ai)
; #pragma unroll
;                 for (int m = 0; m < 4; ++m) { bf16_t* rowp = ZX + (size_t)(row0 + ai * 128 + m * 16) * LDZ + col0;
; #pragma unroll
;                     for (int bj = 0; bj < 2; ++bj) { const f32x4 v0 = acc[ai][bj][m][0], v1 = acc[ai][bj][m][1];
;                         u32x4 o; o.x = pk2(v0[0], v0[1]); o.y = pk2(v0[2], v0[3]); o.z = pk2(v1[0], v1[1]); o.w = pk2(v1[2], v1[3]);
;                         *(u32x4*)(rowp + bj * 128) = o; } }
;         } else if (wc == 0) {
; #pragma unroll
;             for (int ai = 0; ai < 2; ++ai)
; #pragma unroll
;                 for (int m = 0; m < 4; ++m) { float* rowp = DT + (size_t)(row0 + ai * 128 + m * 16) * 32 + 8 * fq;
;                     *(f32x4*)(rowp) = acc[ai][0][m][0]; *(f32x4*)(rowp + 4) = acc[ai][0][m][1]; }
.LBB0_353:
	s_mov_b32 s97, 1
	v_or_b32_e32 v168, 16, v164
	v_ashrrev_i32_e32 v165, 31, v164
	v_ashrrev_i32_e32 v169, 31, v168
	v_lshlrev_b64 v[166:167], 7, v[164:165]
	v_lshlrev_b64 v[168:169], 7, v[168:169]
	v_lshl_add_u64 v[166:167], v[158:159], 0, v[166:167]
	v_lshl_add_u64 v[168:169], v[158:159], 0, v[168:169]
	global_store_dwordx4 v[166:167], v[126:129], off
	global_store_dwordx4 v[166:167], v[122:125], off offset:16
	global_store_dwordx4 v[168:169], v[118:121], off
	global_store_dwordx4 v[168:169], v[110:113], off offset:16
	v_or_b32_e32 v168, 32, v164
	v_ashrrev_i32_e32 v169, 31, v168
	v_lshlrev_b64 v[168:169], 7, v[168:169]
	v_lshl_add_u64 v[168:169], v[158:159], 0, v[168:169]
	global_store_dwordx4 v[168:169], v[102:105], off
	global_store_dwordx4 v[168:169], v[94:97], off offset:16
	v_or_b32_e32 v168, 48, v164
	v_ashrrev_i32_e32 v169, 31, v168
	v_lshlrev_b64 v[168:169], 7, v[168:169]
	v_lshl_add_u64 v[168:169], v[158:159], 0, v[168:169]
	s_mov_b64 s[4:5], 0x4000
	v_add_co_u32_e32 v172, vcc, 0x4000, v166
	global_store_dwordx4 v[168:169], v[86:89], off
	global_store_dwordx4 v[168:169], v[78:81], off offset:16
	v_lshl_add_u64 v[168:169], v[166:167], 0, s[4:5]
	v_addc_co_u32_e32 v173, vcc, 0, v167, vcc
	s_mov_b64 s[4:5], 0x4800
	global_store_dwordx4 v[172:173], v[62:65], off
	global_store_dwordx4 v[168:169], v[58:61], off offset:16
	v_lshl_add_u64 v[168:169], v[166:167], 0, s[4:5]
	global_store_dwordx4 v[172:173], v[54:57], off offset:2048
	global_store_dwordx4 v[168:169], v[46:49], off offset:16
	s_mov_b64 s[4:5], 0x5000
	v_add_co_u32_e32 v172, vcc, 0x5000, v166
	v_lshl_add_u64 v[168:169], v[166:167], 0, s[4:5]
	s_nop 0
	v_addc_co_u32_e32 v173, vcc, 0, v167, vcc
	s_mov_b64 s[4:5], 0x5800
	global_store_dwordx4 v[172:173], v[38:41], off
	global_store_dwordx4 v[168:169], v[30:33], off offset:16
	v_lshl_add_u64 v[166:167], v[166:167], 0, s[4:5]
	global_store_dwordx4 v[172:173], v[22:25], off offset:2048
	global_store_dwordx4 v[166:167], v[14:17], off offset:16
	s_cbranch_execnz .LBB0_349
.LBB0_354:
	s_mov_b32 s97, 1
	v_lshl_or_b32 v168, s36, 8, v170
	v_ashrrev_i32_e32 v169, 31, v168
	v_mov_b64_e32 v[166:167], s[90:91]
	v_cvt_pk_bf16_f32 v70, v70, v71
	v_cvt_pk_bf16_f32 v71, v72, v73
	v_cvt_pk_bf16_f32 v72, v66, v67
	v_add_u32_e32 v66, 0x80, v164
	v_mad_i64_i32 v[172:173], s[4:5], v164, s56, v[166:167]
	v_lshlrev_b64 v[168:169], 1, v[168:169]
	v_cvt_pk_bf16_f32 v114, v114, v115
	v_cvt_pk_bf16_f32 v115, v116, v117
	v_cvt_pk_bf16_f32 v116, v106, v107
	v_or_b32_e32 v106, 16, v164
	v_mad_i64_i32 v[66:67], s[4:5], v66, s56, v[166:167]
	v_cvt_pk_bf16_f32 v50, v50, v51
	v_cvt_pk_bf16_f32 v51, v52, v53
	v_cvt_pk_bf16_f32 v52, v42, v43
	v_add_u32_e32 v42, 0x90, v164
	v_lshl_add_u64 v[172:173], v[172:173], 0, v[168:169]
	v_mad_i64_i32 v[106:107], s[4:5], v106, s56, v[166:167]
	v_cvt_pk_bf16_f32 v98, v98, v99
	v_cvt_pk_bf16_f32 v99, v100, v101
	v_cvt_pk_bf16_f32 v100, v90, v91
	v_or_b32_e32 v90, 32, v164
	v_lshl_add_u64 v[66:67], v[66:67], 0, v[168:169]
	v_mad_i64_i32 v[42:43], s[4:5], v42, s56, v[166:167]
	v_cvt_pk_bf16_f32 v34, v34, v35
	v_cvt_pk_bf16_f32 v35, v36, v37
	v_cvt_pk_bf16_f32 v36, v26, v27
	v_add_u32_e32 v26, 0xa0, v164
	v_cvt_pk_bf16_f32 v117, v108, v109
	global_store_dwordx4 v[172:173], v[114:117], off offset:256
	v_mad_i64_i32 v[90:91], s[4:5], v90, s56, v[166:167]
	s_nop 0
	v_lshl_add_u64 v[114:115], v[106:107], 0, v[168:169]
	v_cvt_pk_bf16_f32 v82, v82, v83
	v_cvt_pk_bf16_f32 v83, v84, v85
	v_cvt_pk_bf16_f32 v84, v74, v75
	v_or_b32_e32 v74, 48, v164
	v_cvt_pk_bf16_f32 v53, v44, v45
	global_store_dwordx4 v[66:67], v[50:53], off offset:256
	v_mad_i64_i32 v[26:27], s[4:5], v26, s56, v[166:167]
	s_nop 0
	v_lshl_add_u64 v[50:51], v[42:43], 0, v[168:169]
	v_cvt_pk_bf16_f32 v18, v18, v19
	v_cvt_pk_bf16_f32 v19, v20, v21
	v_cvt_pk_bf16_f32 v20, v10, v11
	v_add_u32_e32 v10, 0xb0, v164
	v_cvt_pk_bf16_f32 v101, v92, v93
	global_store_dwordx4 v[114:115], v[98:101], off offset:256
	v_mad_i64_i32 v[74:75], s[4:5], v74, s56, v[166:167]
	s_nop 0
	v_lshl_add_u64 v[98:99], v[90:91], 0, v[168:169]
	v_cvt_pk_bf16_f32 v37, v28, v29
	global_store_dwordx4 v[50:51], v[34:37], off offset:256
	v_mad_i64_i32 v[10:11], s[4:5], v10, s56, v[166:167]
	s_nop 0
	v_lshl_add_u64 v[34:35], v[26:27], 0, v[168:169]
	v_cvt_pk_bf16_f32 v85, v76, v77
	global_store_dwordx4 v[98:99], v[82:85], off offset:256
	v_cvt_pk_bf16_f32 v21, v12, v13
	global_store_dwordx4 v[34:35], v[18:21], off offset:256
	v_cvt_pk_bf16_f32 v126, v126, v127
	v_cvt_pk_bf16_f32 v127, v128, v129
	v_cvt_pk_bf16_f32 v128, v122, v123
	s_nop 0
	v_lshl_add_u64 v[82:83], v[74:75], 0, v[168:169]
	v_cvt_pk_bf16_f32 v129, v124, v125
	v_lshl_add_u64 v[18:19], v[10:11], 0, v[168:169]
	global_store_dwordx4 v[172:173], v[126:129], off
	v_cvt_pk_bf16_f32 v106, v118, v119
	v_cvt_pk_bf16_f32 v107, v120, v121
	v_cvt_pk_bf16_f32 v108, v110, v111
	v_cvt_pk_bf16_f32 v109, v112, v113
	global_store_dwordx4 v[114:115], v[106:109], off
	v_cvt_pk_bf16_f32 v90, v102, v103
	v_cvt_pk_bf16_f32 v91, v104, v105
	v_cvt_pk_bf16_f32 v92, v94, v95
	v_cvt_pk_bf16_f32 v93, v96, v97
	global_store_dwordx4 v[98:99], v[90:93], off
	v_cvt_pk_bf16_f32 v74, v86, v87
	v_cvt_pk_bf16_f32 v75, v88, v89
	v_cvt_pk_bf16_f32 v76, v78, v79
	v_cvt_pk_bf16_f32 v77, v80, v81
	global_store_dwordx4 v[82:83], v[74:77], off
	v_cvt_pk_bf16_f32 v73, v68, v69
	global_store_dwordx4 v[82:83], v[70:73], off offset:256
	v_cvt_pk_bf16_f32 v62, v62, v63
	v_cvt_pk_bf16_f32 v63, v64, v65
	v_cvt_pk_bf16_f32 v64, v58, v59
	v_cvt_pk_bf16_f32 v65, v60, v61
	global_store_dwordx4 v[66:67], v[62:65], off
	v_cvt_pk_bf16_f32 v42, v54, v55
	v_cvt_pk_bf16_f32 v43, v56, v57
	v_cvt_pk_bf16_f32 v44, v46, v47
	v_cvt_pk_bf16_f32 v45, v48, v49
	global_store_dwordx4 v[50:51], v[42:45], off
	v_cvt_pk_bf16_f32 v26, v38, v39
	v_cvt_pk_bf16_f32 v27, v40, v41
	v_cvt_pk_bf16_f32 v28, v30, v31
	v_cvt_pk_bf16_f32 v29, v32, v33
	global_store_dwordx4 v[34:35], v[26:29], off
	v_cvt_pk_bf16_f32 v10, v22, v23
	v_cvt_pk_bf16_f32 v11, v24, v25
	v_cvt_pk_bf16_f32 v12, v14, v15
	v_cvt_pk_bf16_f32 v13, v16, v17
	global_store_dwordx4 v[18:19], v[10:13], off
	v_cvt_pk_bf16_f32 v6, v6, v7
	v_cvt_pk_bf16_f32 v7, v8, v9
	v_cvt_pk_bf16_f32 v8, v2, v3
	v_cvt_pk_bf16_f32 v9, v4, v5
	global_store_dwordx4 v[18:19], v[6:9], off offset:256
	s_and_b64 vcc, exec, s[0:1]
	s_mov_b64 s[0:1], -1
	s_cbranch_vccnz .LBB0_337

; __device__ __forceinline__ unsigned pk2(float lo, float hi) { unsigned r; asm("v_cvt_pk_bf16_f32 %0, %1, %2" : "=v"(r) : "v"(lo), "v"(hi)); return r; }
; __device__ __forceinline__ float silu_f(float v) { return v * __builtin_amdgcn_rcpf(1.f + __expf(-v)); }
; __device__ __forceinline__ void conv_rows(const u32x4 (&rawp)[5], const float* wl, float (&o0)[8], float (&o1)[8]) {
;     float raw[5][8];
; #pragma unroll
;     for (int q = 0; q < 5; ++q) unpack8(rawp[q], raw[q]);
; #pragma unroll
;     for (int h = 0; h < 2; ++h) {
;         const f32x4 bv = *(const f32x4*)(wl + 4 * 128 + h * 4);
;         f32x4 a0 = bv, a1 = bv;
; #pragma unroll
;         for (int k = 0; k < 4; ++k) { const f32x4 wv = *(const f32x4*)(wl + k * 128 + h * 4);
; #pragma unroll
;             for (int i = 0; i < 4; ++i) { a0[i] += wv[i] * raw[k][h * 4 + i]; a1[i] += wv[i] * raw[k + 1][h * 4 + i]; } }
; #pragma unroll
;         for (int i = 0; i < 4; ++i) { o0[h * 4 + i] = silu_f(a0[i]); o1[h * 4 + i] = silu_f(a1[i]); }
; __device__ __forceinline__ void phase_ssd(const Params& p, uchar* sm, int j, bf16_t* zx, const float* dtraw, float* ssqb) {
;     ...
;             for (int i = 0; i < 8; ++i) *(unsigned*)(sm + L_XT + (c8 * 8 + i) * RS_T + ((lp ^ swz) * 4)) = pk2(xo0[i], xo1[i]);
.LBB0_466:
	ds_read_b128 v[132:135], v187 offset:2048
	ds_read_b128 v[96:99], v187 offset:0
	ds_read_b128 v[120:123], v187 offset:512
	ds_read_b128 v[124:127], v187 offset:1024
	ds_read_b128 v[128:131], v187 offset:1536
	s_nop 0
	v_lshlrev_b32_e32 v100, 16, v4
	v_and_b32_e32 v101, 0xffff0000, v4
	v_lshlrev_b32_e32 v118, 16, v5
	v_and_b32_e32 v119, 0xffff0000, v5
	s_waitcnt lgkmcnt(3)
	v_pk_fma_f32 v[144:145], v[96:97], v[100:101], v[132:133]
	v_pk_fma_f32 v[178:179], v[98:99], v[118:119], v[134:135]
	v_lshlrev_b32_e32 v100, 16, v8
	v_and_b32_e32 v101, 0xffff0000, v8
	v_lshlrev_b32_e32 v118, 16, v9
	v_and_b32_e32 v119, 0xffff0000, v9
	s_waitcnt lgkmcnt(2)
	v_pk_fma_f32 v[144:145], v[120:121], v[100:101], v[144:145]
	v_pk_fma_f32 v[178:179], v[122:123], v[118:119], v[178:179]
	v_pk_fma_f32 v[180:181], v[96:97], v[100:101], v[132:133]
	v_pk_fma_f32 v[230:231], v[98:99], v[118:119], v[134:135]
	v_lshlrev_b32_e32 v100, 16, v12
	v_and_b32_e32 v101, 0xffff0000, v12
	v_lshlrev_b32_e32 v118, 16, v13
	v_and_b32_e32 v119, 0xffff0000, v13
	s_waitcnt lgkmcnt(1)
	v_pk_fma_f32 v[144:145], v[124:125], v[100:101], v[144:145]
	v_pk_fma_f32 v[178:179], v[126:127], v[118:119], v[178:179]
	v_pk_fma_f32 v[180:181], v[120:121], v[100:101], v[180:181]
	v_pk_fma_f32 v[230:231], v[122:123], v[118:119], v[230:231]
	v_lshlrev_b32_e32 v100, 16, v16
	v_and_b32_e32 v101, 0xffff0000, v16
	v_lshlrev_b32_e32 v118, 16, v17
	v_and_b32_e32 v119, 0xffff0000, v17
	s_waitcnt lgkmcnt(0)
	v_pk_fma_f32 v[144:145], v[128:129], v[100:101], v[144:145]
	v_pk_fma_f32 v[178:179], v[130:131], v[118:119], v[178:179]
	v_pk_fma_f32 v[180:181], v[124:125], v[100:101], v[180:181]
	v_pk_fma_f32 v[230:231], v[126:127], v[118:119], v[230:231]
	v_lshlrev_b32_e32 v100, 16, v24
	v_and_b32_e32 v101, 0xffff0000, v24
	v_lshlrev_b32_e32 v118, 16, v25
	v_and_b32_e32 v119, 0xffff0000, v25
	v_pk_fma_f32 v[180:181], v[128:129], v[100:101], v[180:181]
	v_pk_fma_f32 v[230:231], v[130:131], v[118:119], v[230:231]
	v_pk_mul_f32 v[96:97], v[144:145], s[98:99]
	v_pk_mul_f32 v[98:99], v[178:179], s[98:99]
	v_pk_mul_f32 v[120:121], v[180:181], s[98:99]
	v_pk_mul_f32 v[122:123], v[230:231], s[98:99]
	v_exp_f32_e32 v96, v96
	v_exp_f32_e32 v97, v97
	v_exp_f32_e32 v98, v98
	v_exp_f32_e32 v99, v99
	v_exp_f32_e32 v120, v120
	v_exp_f32_e32 v121, v121
	v_exp_f32_e32 v122, v122
	v_exp_f32_e32 v123, v123
	v_pk_add_f32 v[96:97], v[96:97], s[100:101]
	v_pk_add_f32 v[98:99], v[98:99], s[100:101]
	v_pk_add_f32 v[120:121], v[120:121], s[100:101]
	v_pk_add_f32 v[122:123], v[122:123], s[100:101]
	ds_read_b128 v[132:135], v187 offset:2064
	ds_read_b128 v[112:115], v187 offset:16
	v_rcp_f32_e32 v96, v96
	v_rcp_f32_e32 v97, v97
	v_rcp_f32_e32 v98, v98
	ds_read_b128 v[232:235], v187 offset:528
	v_rcp_f32_e32 v99, v99
	v_rcp_f32_e32 v120, v120
	v_rcp_f32_e32 v121, v121
	v_rcp_f32_e32 v122, v122
	ds_read_b128 v[124:127], v187 offset:1040
	v_rcp_f32_e32 v123, v123
	v_pk_mul_f32 v[104:105], v[144:145], v[96:97]
	v_pk_mul_f32 v[106:107], v[178:179], v[98:99]
	v_pk_mul_f32 v[102:103], v[180:181], v[120:121]
	ds_read_b128 v[128:131], v187 offset:1552
	v_pk_mul_f32 v[108:109], v[230:231], v[122:123]
	v_lshlrev_b32_e32 v100, 16, v6
	v_and_b32_e32 v101, 0xffff0000, v6
	v_lshlrev_b32_e32 v118, 16, v7
	v_and_b32_e32 v119, 0xffff0000, v7
	s_waitcnt lgkmcnt(3)
	v_pk_fma_f32 v[144:145], v[112:113], v[100:101], v[132:133]
	v_pk_fma_f32 v[178:179], v[114:115], v[118:119], v[134:135]
	v_lshlrev_b32_e32 v100, 16, v10
	v_and_b32_e32 v101, 0xffff0000, v10
	v_lshlrev_b32_e32 v118, 16, v11
	v_and_b32_e32 v119, 0xffff0000, v11
	s_waitcnt lgkmcnt(2)
	v_pk_fma_f32 v[144:145], v[232:233], v[100:101], v[144:145]
	v_pk_fma_f32 v[178:179], v[234:235], v[118:119], v[178:179]
	v_pk_fma_f32 v[180:181], v[112:113], v[100:101], v[132:133]
	v_pk_fma_f32 v[230:231], v[114:115], v[118:119], v[134:135]
	v_lshlrev_b32_e32 v100, 16, v14
	v_and_b32_e32 v101, 0xffff0000, v14
	v_lshlrev_b32_e32 v118, 16, v15
	v_and_b32_e32 v119, 0xffff0000, v15
	s_waitcnt lgkmcnt(1)
	v_pk_fma_f32 v[144:145], v[124:125], v[100:101], v[144:145]
	v_pk_fma_f32 v[178:179], v[126:127], v[118:119], v[178:179]
	v_pk_fma_f32 v[180:181], v[232:233], v[100:101], v[180:181]
	v_pk_fma_f32 v[230:231], v[234:235], v[118:119], v[230:231]
	v_lshlrev_b32_e32 v100, 16, v18
	v_and_b32_e32 v101, 0xffff0000, v18
	v_lshlrev_b32_e32 v118, 16, v19
	v_and_b32_e32 v119, 0xffff0000, v19
	s_waitcnt lgkmcnt(0)
	v_pk_fma_f32 v[144:145], v[128:129], v[100:101], v[144:145]
	v_pk_fma_f32 v[178:179], v[130:131], v[118:119], v[178:179]
	v_pk_fma_f32 v[180:181], v[124:125], v[100:101], v[180:181]
	v_pk_fma_f32 v[230:231], v[126:127], v[118:119], v[230:231]
	v_lshlrev_b32_e32 v100, 16, v26
	v_and_b32_e32 v101, 0xffff0000, v26
	v_lshlrev_b32_e32 v118, 16, v27
	v_and_b32_e32 v119, 0xffff0000, v27
	v_pk_fma_f32 v[180:181], v[128:129], v[100:101], v[180:181]
	v_pk_fma_f32 v[230:231], v[130:131], v[118:119], v[230:231]
	v_pk_mul_f32 v[96:97], v[144:145], s[98:99]
	v_pk_mul_f32 v[98:99], v[178:179], s[98:99]
	v_pk_mul_f32 v[120:121], v[180:181], s[98:99]
	v_pk_mul_f32 v[122:123], v[230:231], s[98:99]
	v_exp_f32_e32 v96, v96
	v_exp_f32_e32 v97, v97
	v_exp_f32_e32 v98, v98
	v_exp_f32_e32 v99, v99
	v_exp_f32_e32 v120, v120
	v_exp_f32_e32 v121, v121
	v_exp_f32_e32 v122, v122
	v_exp_f32_e32 v123, v123
	v_pk_add_f32 v[96:97], v[96:97], s[100:101]
	v_pk_add_f32 v[98:99], v[98:99], s[100:101]
	v_pk_add_f32 v[120:121], v[120:121], s[100:101]
	v_pk_add_f32 v[122:123], v[122:123], s[100:101]
	v_rcp_f32_e32 v96, v96
	v_rcp_f32_e32 v97, v97
	v_rcp_f32_e32 v98, v98
	v_rcp_f32_e32 v99, v99
	v_rcp_f32_e32 v120, v120
	v_rcp_f32_e32 v121, v121
	v_rcp_f32_e32 v122, v122
	v_rcp_f32_e32 v123, v123
	v_pk_mul_f32 v[110:111], v[144:145], v[96:97]
	v_pk_mul_f32 v[112:113], v[178:179], v[98:99]
	v_pk_mul_f32 v[114:115], v[180:181], v[120:121]
	v_pk_mul_f32 v[116:117], v[230:231], v[122:123]
	v_cvt_pk_bf16_f32 v96, v104, v102
	v_cvt_pk_bf16_f32 v97, v105, v103
	v_add_u32_e32 v98, 0xd000, v206
	ds_write2_b32 v98, v96, v97 offset1:36
	v_cvt_pk_bf16_f32 v96, v106, v108
	v_cvt_pk_bf16_f32 v97, v107, v109
	ds_write2_b32 v98, v96, v97 offset0:72 offset1:108
	v_cvt_pk_bf16_f32 v96, v110, v114
	v_cvt_pk_bf16_f32 v97, v111, v115
	ds_write2_b32 v98, v96, v97 offset0:144 offset1:180
	v_cvt_pk_bf16_f32 v96, v112, v116
	v_cvt_pk_bf16_f32 v97, v113, v117
	ds_write2_b32 v98, v96, v97 offset0:216 offset1:252
	ds_read_b128 v[232:235], v187 offset:4608
	ds_read_b128 v[96:99], v187 offset:2560
	ds_read_b128 v[124:127], v187 offset:3072
	ds_read_b128 v[128:131], v187 offset:3584
	ds_read_b128 v[132:135], v187 offset:4096
	s_waitcnt vmcnt(2)
; __device__ __forceinline__ unsigned pk2(float lo, float hi) { unsigned r; asm("v_cvt_pk_bf16_f32 %0, %1, %2" : "=v"(r) : "v"(lo), "v"(hi)); return r; }
; __device__ __forceinline__ u32x4 pack8(const float (&o)[8]) { u32x4 r; r.x = pk2(o[0], o[1]); r.y = pk2(o[2], o[3]); r.z = pk2(o[4], o[5]); r.w = pk2(o[6], o[7]); return r; }
; __device__ __forceinline__ void phase_ssd(const Params& p, uchar* sm, int j, bf16_t* zx, const float* dtraw, float* ssqb) {
;     ...
;                 conv_rows(rb, wlb, t0, t1);
;                 __builtin_amdgcn_sched_barrier(0);
;                 *(u32x4*)(sm + L_B + (2 * lp) * RS_CB + c8 * 16) = pack8(t0);
;                 *(u32x4*)(sm + L_B + (2 * lp + 1) * RS_CB + c8 * 16) = pack8(t1);
; #pragma unroll
;                 for (int i = 0; i < 8; ++i) *(unsigned*)(sm + L_BT + (c8 * 8 + i) * RS_T + ((lp ^ swz) * 4)) = pk2(t0[i], t1[i]);
	v_lshlrev_b32_e32 v144, 16, v20
	v_and_b32_e32 v145, 0xffff0000, v20
	v_lshlrev_b32_e32 v178, 16, v21
	v_and_b32_e32 v179, 0xffff0000, v21
	s_waitcnt lgkmcnt(3)
	v_pk_fma_f32 v[180:181], v[96:97], v[144:145], v[232:233]
	v_pk_fma_f32 v[230:231], v[98:99], v[178:179], v[234:235]
	v_lshlrev_b32_e32 v144, 16, v28
	v_and_b32_e32 v145, 0xffff0000, v28
	v_lshlrev_b32_e32 v178, 16, v29
	v_and_b32_e32 v179, 0xffff0000, v29
	s_waitcnt lgkmcnt(2)
	v_pk_fma_f32 v[180:181], v[124:125], v[144:145], v[180:181]
	v_pk_fma_f32 v[230:231], v[126:127], v[178:179], v[230:231]
	v_pk_fma_f32 v[236:237], v[96:97], v[144:145], v[232:233]
	v_pk_fma_f32 v[238:239], v[98:99], v[178:179], v[234:235]
	v_lshlrev_b32_e32 v144, 16, v32
	v_and_b32_e32 v145, 0xffff0000, v32
	v_lshlrev_b32_e32 v178, 16, v33
	v_and_b32_e32 v179, 0xffff0000, v33
	s_waitcnt lgkmcnt(1)
	v_pk_fma_f32 v[180:181], v[128:129], v[144:145], v[180:181]
	v_pk_fma_f32 v[230:231], v[130:131], v[178:179], v[230:231]
	v_pk_fma_f32 v[236:237], v[124:125], v[144:145], v[236:237]
	v_pk_fma_f32 v[238:239], v[126:127], v[178:179], v[238:239]
	v_lshlrev_b32_e32 v144, 16, v36
	v_and_b32_e32 v145, 0xffff0000, v36
	v_lshlrev_b32_e32 v178, 16, v37
	v_and_b32_e32 v179, 0xffff0000, v37
	s_waitcnt lgkmcnt(0)
	v_pk_fma_f32 v[180:181], v[132:133], v[144:145], v[180:181]
	v_pk_fma_f32 v[230:231], v[134:135], v[178:179], v[230:231]
	v_pk_fma_f32 v[236:237], v[128:129], v[144:145], v[236:237]
	v_pk_fma_f32 v[238:239], v[130:131], v[178:179], v[238:239]
	v_lshlrev_b32_e32 v144, 16, v40
	v_and_b32_e32 v145, 0xffff0000, v40
	v_lshlrev_b32_e32 v178, 16, v41
	v_and_b32_e32 v179, 0xffff0000, v41
	v_pk_fma_f32 v[236:237], v[132:133], v[144:145], v[236:237]
	v_pk_fma_f32 v[238:239], v[134:135], v[178:179], v[238:239]
	v_pk_mul_f32 v[96:97], v[180:181], s[98:99]
	v_pk_mul_f32 v[98:99], v[230:231], s[98:99]
	v_pk_mul_f32 v[124:125], v[236:237], s[98:99]
	v_pk_mul_f32 v[126:127], v[238:239], s[98:99]
	v_exp_f32_e32 v96, v96
	v_exp_f32_e32 v97, v97
	v_exp_f32_e32 v98, v98
	v_exp_f32_e32 v99, v99
	v_exp_f32_e32 v124, v124
	v_exp_f32_e32 v125, v125
	v_exp_f32_e32 v126, v126
	v_exp_f32_e32 v127, v127
	v_pk_add_f32 v[96:97], v[96:97], s[100:101]
	v_pk_add_f32 v[98:99], v[98:99], s[100:101]
	v_pk_add_f32 v[124:125], v[124:125], s[100:101]
	v_pk_add_f32 v[126:127], v[126:127], s[100:101]
	ds_read_b128 v[232:235], v187 offset:4624
	ds_read_b128 v[120:123], v187 offset:2576
	v_rcp_f32_e32 v96, v96
	v_rcp_f32_e32 v97, v97
	v_rcp_f32_e32 v98, v98
	ds_read_b128 v[248:251], v187 offset:3088
	v_rcp_f32_e32 v99, v99
	v_rcp_f32_e32 v124, v124
	v_rcp_f32_e32 v125, v125
	v_rcp_f32_e32 v126, v126
	ds_read_b128 v[128:131], v187 offset:3600
	v_rcp_f32_e32 v127, v127
	v_pk_mul_f32 v[240:241], v[180:181], v[96:97]
	v_pk_mul_f32 v[246:247], v[230:231], v[98:99]
	v_pk_mul_f32 v[242:243], v[236:237], v[124:125]
	ds_read_b128 v[132:135], v187 offset:4112
	v_pk_mul_f32 v[252:253], v[238:239], v[126:127]
	v_lshlrev_b32_e32 v144, 16, v22
	v_and_b32_e32 v145, 0xffff0000, v22
	v_lshlrev_b32_e32 v178, 16, v23
	v_and_b32_e32 v179, 0xffff0000, v23
	s_waitcnt lgkmcnt(3)
	v_pk_fma_f32 v[180:181], v[120:121], v[144:145], v[232:233]
	v_pk_fma_f32 v[230:231], v[122:123], v[178:179], v[234:235]
	v_lshlrev_b32_e32 v144, 16, v30
	v_and_b32_e32 v145, 0xffff0000, v30
	v_lshlrev_b32_e32 v178, 16, v31
	v_and_b32_e32 v179, 0xffff0000, v31
	s_waitcnt lgkmcnt(2)
	v_pk_fma_f32 v[180:181], v[248:249], v[144:145], v[180:181]
	v_pk_fma_f32 v[230:231], v[250:251], v[178:179], v[230:231]
	v_pk_fma_f32 v[236:237], v[120:121], v[144:145], v[232:233]
	v_pk_fma_f32 v[238:239], v[122:123], v[178:179], v[234:235]
	v_lshlrev_b32_e32 v144, 16, v34
	v_and_b32_e32 v145, 0xffff0000, v34
	v_lshlrev_b32_e32 v178, 16, v35
	v_and_b32_e32 v179, 0xffff0000, v35
	s_waitcnt lgkmcnt(1)
	v_pk_fma_f32 v[180:181], v[128:129], v[144:145], v[180:181]
	v_pk_fma_f32 v[230:231], v[130:131], v[178:179], v[230:231]
	v_pk_fma_f32 v[236:237], v[248:249], v[144:145], v[236:237]
	v_pk_fma_f32 v[238:239], v[250:251], v[178:179], v[238:239]
	v_lshlrev_b32_e32 v144, 16, v38
	v_and_b32_e32 v145, 0xffff0000, v38
	v_lshlrev_b32_e32 v178, 16, v39
	v_and_b32_e32 v179, 0xffff0000, v39
	s_waitcnt lgkmcnt(0)
	v_pk_fma_f32 v[180:181], v[132:133], v[144:145], v[180:181]
	v_pk_fma_f32 v[230:231], v[134:135], v[178:179], v[230:231]
	v_pk_fma_f32 v[236:237], v[128:129], v[144:145], v[236:237]
	v_pk_fma_f32 v[238:239], v[130:131], v[178:179], v[238:239]
	v_lshlrev_b32_e32 v144, 16, v42
	v_and_b32_e32 v145, 0xffff0000, v42
	v_lshlrev_b32_e32 v178, 16, v43
	v_and_b32_e32 v179, 0xffff0000, v43
	v_pk_fma_f32 v[236:237], v[132:133], v[144:145], v[236:237]
	v_pk_fma_f32 v[238:239], v[134:135], v[178:179], v[238:239]
	v_pk_mul_f32 v[96:97], v[180:181], s[98:99]
	v_pk_mul_f32 v[98:99], v[230:231], s[98:99]
	v_pk_mul_f32 v[124:125], v[236:237], s[98:99]
	v_pk_mul_f32 v[126:127], v[238:239], s[98:99]
	v_exp_f32_e32 v96, v96
	v_exp_f32_e32 v97, v97
	v_exp_f32_e32 v98, v98
	v_exp_f32_e32 v99, v99
	v_exp_f32_e32 v124, v124
	v_exp_f32_e32 v125, v125
	v_exp_f32_e32 v126, v126
	v_exp_f32_e32 v127, v127
	v_pk_add_f32 v[96:97], v[96:97], s[100:101]
	v_pk_add_f32 v[98:99], v[98:99], s[100:101]
	v_pk_add_f32 v[124:125], v[124:125], s[100:101]
	v_pk_add_f32 v[126:127], v[126:127], s[100:101]
	v_rcp_f32_e32 v96, v96
	v_rcp_f32_e32 v97, v97
	v_rcp_f32_e32 v98, v98
	v_rcp_f32_e32 v99, v99
	v_rcp_f32_e32 v124, v124
	v_rcp_f32_e32 v125, v125
	v_rcp_f32_e32 v126, v126
	v_rcp_f32_e32 v127, v127
	v_pk_mul_f32 v[120:121], v[180:181], v[96:97]
	v_pk_mul_f32 v[118:119], v[230:231], v[98:99]
	v_pk_mul_f32 v[122:123], v[236:237], v[124:125]
	v_pk_mul_f32 v[100:101], v[238:239], v[126:127]
	v_cvt_pk_bf16_f32 v96, v240, v241
	v_cvt_pk_bf16_f32 v97, v246, v247
	v_cvt_pk_bf16_f32 v98, v120, v121
	v_cvt_pk_bf16_f32 v99, v118, v119
	ds_write_b128 v207, v[96:99] offset:17408
	v_cvt_pk_bf16_f32 v96, v242, v243
	v_cvt_pk_bf16_f32 v97, v252, v253
	v_cvt_pk_bf16_f32 v98, v122, v123
	v_cvt_pk_bf16_f32 v99, v100, v101
	ds_write_b128 v208, v[96:99] offset:17408
	v_cvt_pk_bf16_f32 v96, v240, v242
	v_cvt_pk_bf16_f32 v97, v241, v243
	v_add_u32_e32 v98, 0x8800, v206
	ds_write2_b32 v98, v96, v97 offset1:36
	v_cvt_pk_bf16_f32 v96, v246, v252
	v_cvt_pk_bf16_f32 v97, v247, v253
	ds_write2_b32 v98, v96, v97 offset0:72 offset1:108
	v_cvt_pk_bf16_f32 v96, v120, v122
	v_cvt_pk_bf16_f32 v97, v121, v123
	ds_write2_b32 v98, v96, v97 offset0:144 offset1:180
	v_cvt_pk_bf16_f32 v96, v118, v100
	v_cvt_pk_bf16_f32 v97, v119, v101
	ds_write2_b32 v98, v96, v97 offset0:216 offset1:252
	ds_read_b128 v[236:239], v187 offset:7168
	ds_read_b128 v[124:127], v187 offset:5120
	ds_read_b128 v[128:131], v187 offset:5632
	ds_read_b128 v[132:135], v187 offset:6144
	ds_read_b128 v[232:235], v187 offset:6656
	v_lshlrev_b32_e32 v96, 16, v44
	v_and_b32_e32 v97, 0xffff0000, v44
	v_lshlrev_b32_e32 v144, 16, v45
	v_and_b32_e32 v145, 0xffff0000, v45
	s_waitcnt lgkmcnt(3)
; __device__ __forceinline__ u32x4 pack8(const float (&o)[8]) { u32x4 r; r.x = pk2(o[0], o[1]); r.y = pk2(o[2], o[3]); r.z = pk2(o[4], o[5]); r.w = pk2(o[6], o[7]); return r; }
; __device__ __forceinline__ void phase_ssd(const Params& p, uchar* sm, int j, bf16_t* zx, const float* dtraw, float* ssqb) {
;     ...
;                 conv_rows(rc, wlc, t0, t1);
;                 __builtin_amdgcn_sched_barrier(0);
;                 *(u32x4*)(sm + L_C + (2 * lp) * RS_CB + c8 * 16) = pack8(t0);
;                 *(u32x4*)(sm + L_C + (2 * lp + 1) * RS_CB + c8 * 16) = pack8(t1);
;             }
;             const u32x4 xp0 = pack8(xo0), xp1 = pack8(xo1);
	v_pk_fma_f32 v[178:179], v[124:125], v[96:97], v[236:237]
	v_pk_fma_f32 v[180:181], v[126:127], v[144:145], v[238:239]
	v_lshlrev_b32_e32 v96, 16, v48
	v_and_b32_e32 v97, 0xffff0000, v48
	v_lshlrev_b32_e32 v144, 16, v49
	v_and_b32_e32 v145, 0xffff0000, v49
	s_waitcnt lgkmcnt(2)
	v_pk_fma_f32 v[178:179], v[128:129], v[96:97], v[178:179]
	v_pk_fma_f32 v[180:181], v[130:131], v[144:145], v[180:181]
	v_pk_fma_f32 v[230:231], v[124:125], v[96:97], v[236:237]
	v_pk_fma_f32 v[246:247], v[126:127], v[144:145], v[238:239]
	v_lshlrev_b32_e32 v96, 16, v52
	v_and_b32_e32 v97, 0xffff0000, v52
	v_lshlrev_b32_e32 v144, 16, v53
	v_and_b32_e32 v145, 0xffff0000, v53
	s_waitcnt lgkmcnt(1)
	v_pk_fma_f32 v[178:179], v[132:133], v[96:97], v[178:179]
	v_pk_fma_f32 v[180:181], v[134:135], v[144:145], v[180:181]
	v_pk_fma_f32 v[230:231], v[128:129], v[96:97], v[230:231]
	v_pk_fma_f32 v[246:247], v[130:131], v[144:145], v[246:247]
	v_lshlrev_b32_e32 v96, 16, v56
	v_and_b32_e32 v97, 0xffff0000, v56
	v_lshlrev_b32_e32 v144, 16, v57
	v_and_b32_e32 v145, 0xffff0000, v57
	s_waitcnt lgkmcnt(0)
	v_pk_fma_f32 v[178:179], v[232:233], v[96:97], v[178:179]
	v_pk_fma_f32 v[180:181], v[234:235], v[144:145], v[180:181]
	v_pk_fma_f32 v[230:231], v[132:133], v[96:97], v[230:231]
	v_pk_fma_f32 v[246:247], v[134:135], v[144:145], v[246:247]
	v_lshlrev_b32_e32 v96, 16, v60
	v_and_b32_e32 v97, 0xffff0000, v60
	v_lshlrev_b32_e32 v144, 16, v61
	v_and_b32_e32 v145, 0xffff0000, v61
	v_pk_fma_f32 v[230:231], v[232:233], v[96:97], v[230:231]
	v_pk_fma_f32 v[246:247], v[234:235], v[144:145], v[246:247]
	v_pk_mul_f32 v[124:125], v[178:179], s[98:99]
	v_pk_mul_f32 v[126:127], v[180:181], s[98:99]
	v_pk_mul_f32 v[128:129], v[230:231], s[98:99]
	v_pk_mul_f32 v[130:131], v[246:247], s[98:99]
	v_exp_f32_e32 v124, v124
	v_exp_f32_e32 v125, v125
	v_exp_f32_e32 v126, v126
	v_exp_f32_e32 v127, v127
	v_exp_f32_e32 v128, v128
	v_exp_f32_e32 v129, v129
	v_exp_f32_e32 v130, v130
	v_exp_f32_e32 v131, v131
	v_pk_add_f32 v[124:125], v[124:125], s[100:101]
	v_pk_add_f32 v[126:127], v[126:127], s[100:101]
	v_pk_add_f32 v[128:129], v[128:129], s[100:101]
	v_pk_add_f32 v[130:131], v[130:131], s[100:101]
	ds_read_b128 v[236:239], v187 offset:7184
	ds_read_b128 v[120:123], v187 offset:5136
	v_rcp_f32_e32 v124, v124
	v_rcp_f32_e32 v125, v125
	v_rcp_f32_e32 v126, v126
	ds_read_b128 v[248:251], v187 offset:5648
	v_rcp_f32_e32 v127, v127
	v_rcp_f32_e32 v128, v128
	v_rcp_f32_e32 v129, v129
	v_rcp_f32_e32 v130, v130
	ds_read_b128 v[132:135], v187 offset:6160
	v_rcp_f32_e32 v131, v131
	v_mul_f32_e32 v139, v178, v124
	v_mul_f32_e32 v170, v179, v125
	v_pk_mul_f32 v[240:241], v[180:181], v[126:127]
	v_pk_mul_f32 v[242:243], v[230:231], v[128:129]
	ds_read_b128 v[232:235], v187 offset:6672
	v_pk_mul_f32 v[252:253], v[246:247], v[130:131]
	v_lshlrev_b32_e32 v96, 16, v46
	v_and_b32_e32 v97, 0xffff0000, v46
	v_lshlrev_b32_e32 v144, 16, v47
	v_and_b32_e32 v145, 0xffff0000, v47
	s_waitcnt lgkmcnt(3)
	v_pk_fma_f32 v[178:179], v[120:121], v[96:97], v[236:237]
	v_pk_fma_f32 v[180:181], v[122:123], v[144:145], v[238:239]
	v_lshlrev_b32_e32 v96, 16, v50
	v_and_b32_e32 v97, 0xffff0000, v50
	v_lshlrev_b32_e32 v144, 16, v51
	v_and_b32_e32 v145, 0xffff0000, v51
	s_waitcnt lgkmcnt(2)
	v_pk_fma_f32 v[178:179], v[248:249], v[96:97], v[178:179]
	v_pk_fma_f32 v[180:181], v[250:251], v[144:145], v[180:181]
	v_pk_fma_f32 v[230:231], v[120:121], v[96:97], v[236:237]
	v_pk_fma_f32 v[246:247], v[122:123], v[144:145], v[238:239]
	v_lshlrev_b32_e32 v96, 16, v54
	v_and_b32_e32 v97, 0xffff0000, v54
	v_lshlrev_b32_e32 v144, 16, v55
	v_and_b32_e32 v145, 0xffff0000, v55
	s_waitcnt lgkmcnt(1)
	v_pk_fma_f32 v[178:179], v[132:133], v[96:97], v[178:179]
	v_pk_fma_f32 v[180:181], v[134:135], v[144:145], v[180:181]
	v_pk_fma_f32 v[230:231], v[248:249], v[96:97], v[230:231]
	v_pk_fma_f32 v[246:247], v[250:251], v[144:145], v[246:247]
	v_lshlrev_b32_e32 v96, 16, v58
	v_and_b32_e32 v97, 0xffff0000, v58
	v_lshlrev_b32_e32 v144, 16, v59
	v_and_b32_e32 v145, 0xffff0000, v59
	s_waitcnt lgkmcnt(0)
	v_pk_fma_f32 v[178:179], v[232:233], v[96:97], v[178:179]
	v_pk_fma_f32 v[180:181], v[234:235], v[144:145], v[180:181]
	v_pk_fma_f32 v[230:231], v[132:133], v[96:97], v[230:231]
	v_pk_fma_f32 v[246:247], v[134:135], v[144:145], v[246:247]
	v_lshlrev_b32_e32 v96, 16, v62
	v_and_b32_e32 v97, 0xffff0000, v62
	v_lshlrev_b32_e32 v144, 16, v63
	v_and_b32_e32 v145, 0xffff0000, v63
	v_pk_fma_f32 v[230:231], v[232:233], v[96:97], v[230:231]
	v_pk_fma_f32 v[246:247], v[234:235], v[144:145], v[246:247]
	v_pk_mul_f32 v[124:125], v[178:179], s[98:99]
	v_pk_mul_f32 v[126:127], v[180:181], s[98:99]
	v_pk_mul_f32 v[128:129], v[230:231], s[98:99]
	v_pk_mul_f32 v[130:131], v[246:247], s[98:99]
	v_exp_f32_e32 v124, v124
	v_exp_f32_e32 v125, v125
	v_exp_f32_e32 v126, v126
	v_exp_f32_e32 v127, v127
	v_exp_f32_e32 v128, v128
	v_exp_f32_e32 v129, v129
	v_exp_f32_e32 v130, v130
	v_exp_f32_e32 v131, v131
	v_pk_add_f32 v[124:125], v[124:125], s[100:101]
	v_pk_add_f32 v[126:127], v[126:127], s[100:101]
	v_pk_add_f32 v[128:129], v[128:129], s[100:101]
	v_pk_add_f32 v[130:131], v[130:131], s[100:101]
	v_rcp_f32_e32 v124, v124
	v_rcp_f32_e32 v125, v125
	v_rcp_f32_e32 v126, v126
	v_rcp_f32_e32 v127, v127
	v_rcp_f32_e32 v128, v128
	v_rcp_f32_e32 v129, v129
	v_rcp_f32_e32 v130, v130
	v_rcp_f32_e32 v131, v131
	v_mul_f32_e32 v122, v178, v124
	v_mul_f32_e32 v99, v179, v125
	v_pk_mul_f32 v[100:101], v[180:181], v[126:127]
	v_pk_mul_f32 v[118:119], v[230:231], v[128:129]
	v_pk_mul_f32 v[120:121], v[246:247], v[130:131]
	v_readlane_b32 s60, v254, 0
	s_cmp_lg_u32 s83, 1
	v_readlane_b32 s66, v254, 6
	v_readlane_b32 s67, v254, 7
	v_cvt_pk_bf16_f32 v96, v139, v170
	v_cvt_pk_bf16_f32 v97, v240, v241
	v_cvt_pk_bf16_f32 v98, v122, v99
	v_cvt_pk_bf16_f32 v99, v100, v101
	v_cvt_pk_bf16_f32 v235, v104, v105
	v_cvt_pk_bf16_f32 v231, v102, v103
	s_cselect_b64 s[0:1], -1, 0
	s_cmp_eq_u32 s83, 1
	v_lshl_add_u64 v[104:105], s[66:67], 0, v[174:175]
	ds_write_b128 v207, v[96:99]
	v_cvt_pk_bf16_f32 v96, v242, v243
	v_cvt_pk_bf16_f32 v97, v252, v253
	v_cvt_pk_bf16_f32 v98, v118, v119
	v_cvt_pk_bf16_f32 v99, v120, v121
	ds_write_b128 v208, v[96:99]
	v_cvt_pk_bf16_f32 v233, v106, v107
	v_cvt_pk_bf16_f32 v236, v110, v111
	v_cvt_pk_bf16_f32 v234, v112, v113
	v_cvt_pk_bf16_f32 v229, v108, v109
	v_cvt_pk_bf16_f32 v232, v114, v115
	v_cvt_pk_bf16_f32 v230, v116, v117
	v_readlane_b32 s61, v254, 1
	v_readlane_b32 s62, v254, 2
	v_readlane_b32 s63, v254, 3
	v_readlane_b32 s64, v254, 4
	v_readlane_b32 s65, v254, 5
	s_cbranch_scc1 .LBB0_468
; __device__ __forceinline__ void load_raw(const bf16_t* base, int toff, bool first, int lrow, u32x4 (&raw)[5]) {
; #pragma unroll
;     for (int q = 0; q < 5; ++q) {
;         if (!first || lrow - 3 + q >= 0) raw[q] = *(const u32x4*)(base + (q - 3) * LDZ + toff);
;         else raw[q] = (u32x4){0u, 0u, 0u, 0u}; }
; }
; __device__ __forceinline__ void phase_ssd(const Params& p, uchar* sm, int j, bf16_t* zx, const float* dtraw, float* ssqb) {
;     ...
;             if (c + 1 < 32) { const bf16_t* zb = zc + 64 * LDZ;
;                 load_raw(zb + 2048 + colx, toff, false, 2 * lp, rx); }
	v_add_co_u32_e32 v4, vcc, 0x64d5000, v104
	s_nop 1
	v_addc_co_u32_e32 v5, vcc, 0, v105, vcc
	v_add_co_u32_e32 v8, vcc, 0x64d8000, v104
	s_nop 1
	v_addc_co_u32_e32 v9, vcc, 0, v105, vcc
	v_add_co_u32_e32 v12, vcc, 0x64db000, v104
	global_load_dwordx4 v[4:7], v[4:5], off offset:3712
	s_nop 0
	global_load_dwordx4 v[8:11], v[8:9], off offset:3840
	v_addc_co_u32_e32 v13, vcc, 0, v105, vcc
	v_add_co_u32_e32 v16, vcc, 0x64df000, v104
	s_nop 1
	v_addc_co_u32_e32 v17, vcc, 0, v105, vcc
	v_add_co_u32_e32 v24, vcc, 0x64e2000, v104
	global_load_dwordx4 v[12:15], v[12:13], off offset:3968
	s_nop 0
	global_load_dwordx4 v[16:19], v[16:17], off
	v_addc_co_u32_e32 v25, vcc, 0, v105, vcc
	global_load_dwordx4 v[24:27], v[24:25], off offset:128
